# v35 + the same LDS-staged row-contiguous stores in the S=2048 DFT stage-1 loop (group 0)
# baseline (speedup 1.0000x reference)
.LBB0_131:
	s_andn2_b64 vcc, exec, s[8:9]
	s_cbranch_vccnz .LBB0_135
	s_and_b64 vcc, exec, s[40:41]
	s_cbranch_vccnz .LBB0_135
	v_readlane_b32 s6, v245, 20
	v_lshrrev_b32_e32 v2, 2, v201
	v_lshlrev_b32_e32 v3, 3, v201
	v_readlane_b32 s7, v245, 21
	s_add_u32 s3, s6, 0x2a60000
	v_mul_u32_u24_e32 v2, 0x90, v2
	v_and_b32_e32 v3, 24, v3
	v_lshlrev_b32_e32 v154, 3, v177
	v_or_b32_e32 v5, 16, v176
	s_addc_u32 s8, s7, 0
	v_lshlrev_b32_e32 v0, 2, v176
	v_lshl_add_u32 v1, v176, 3, s2
	v_add3_u32 v94, s2, v2, v3
	v_lshlrev_b32_e32 v2, 2, v177
	v_lshl_add_u64 v[84:85], s[4:5], 0, v[154:155]
	v_lshlrev_b32_e32 v96, 7, v177
	v_mul_u32_u24_e32 v3, 0x90, v177
	v_lshlrev_b32_e32 v4, 5, v176
	v_lshlrev_b32_e32 v6, 5, v5
	s_lshl_b32 s2, s23, 6
	v_readlane_b32 s4, v245, 0
	v_and_b32_e32 v95, 1, v200
	v_or_b32_e32 v97, 0x200, v96
	v_or_b32_e32 v98, 0x400, v96
	v_or_b32_e32 v99, 0x600, v96
	v_lshrrev_b32_e32 v100, 1, v176
	v_lshrrev_b32_e32 v101, 1, v5
	s_add_i32 s2, s4, s2
	v_lshlrev_b32_e32 v154, 1, v0
	v_add_u32_e32 v102, v1, v3
	v_lshlrev_b32_e32 v86, 1, v4
	v_lshlrev_b32_e32 v88, 1, v2
	v_lshlrev_b32_e32 v90, 1, v6
	s_mov_b32 s9, s20
	v_readlane_b32 s12, v247, 37
	v_readfirstlane_b32 s100, v102
	s_nop 0
	v_and_b32_e32 v220, 15, v199
	v_lshrrev_b32_e32 v221, 4, v199
	v_mul_u32_u24_e32 v216, 0x90, v220
	v_lshl_add_u32 v216, v221, 3, v216
	v_add_u32_e32 v216, s100, v216
	v_mul_u32_u24_e32 v217, 0x90, v221
	v_lshl_add_u32 v217, v220, 3, v217
	v_add_u32_e32 v217, s100, v217
	v_lshrrev_b32_e32 v222, 1, v221
	v_and_b32_e32 v223, 1, v221
	s_mov_b32 s98, 0x80800
	v_mul_lo_u32 v218, v222, s98
	v_lshl_add_u32 v218, v223, 11, v218
	v_lshl_add_u32 v218, v220, 3, v218
	v_add_u32_e32 v219, 0x101000, v218
	v_add_u32_e32 v228, 0x202000, v218
	v_add_u32_e32 v229, 0x303000, v218
.LBB0_134:
	s_bfe_u32 s10, s9, 0x50004
	s_ashr_i32 s11, s9, 9
	s_lshl_b32 s4, s11, 11
	s_lshl_b32 s5, s10, 2
	s_or_b32 s13, s4, s5
	v_or_b32_e32 v46, s13, v96
	v_mov_b64_e32 v[44:45], s[92:93]
	s_and_b32 s6, s2, 0x3c0
	v_mad_i64_i32 v[0:1], s[4:5], v46, s33, v[44:45]
	s_lshl_b32 s4, s6, 1
	s_mov_b32 s5, s96
	v_lshl_add_u64 v[0:1], v[0:1], 0, s[4:5]
	v_or_b32_e32 v47, s13, v97
	v_lshl_add_u64 v[0:1], v[0:1], 0, v[154:155]
	v_mad_i64_i32 v[2:3], s[6:7], v47, s33, v[44:45]
	v_add_co_u32_e32 v0, vcc, s46, v0
	v_lshl_add_u64 v[2:3], v[2:3], 0, s[4:5]
	v_or_b32_e32 v50, s13, v98
	v_addc_co_u32_e32 v1, vcc, 0, v1, vcc
	v_lshl_add_u64 v[2:3], v[2:3], 0, v[154:155]
	v_mad_i64_i32 v[4:5], s[6:7], v50, s33, v[44:45]
	v_add_co_u32_e32 v2, vcc, s46, v2
	v_lshl_add_u64 v[4:5], v[4:5], 0, s[4:5]
	s_nop 0
	v_addc_co_u32_e32 v3, vcc, 0, v3, vcc
	v_lshl_add_u64 v[4:5], v[4:5], 0, v[154:155]
	v_add_co_u32_e32 v6, vcc, s46, v4
	v_or_b32_e32 v51, s13, v99
	s_nop 0
	v_addc_co_u32_e32 v7, vcc, 0, v5, vcc
	v_mad_i64_i32 v[4:5], s[6:7], v51, s33, v[44:45]
	v_lshl_add_u64 v[4:5], v[4:5], 0, s[4:5]
	v_lshl_add_u64 v[4:5], v[4:5], 0, v[154:155]
	v_add_co_u32_e32 v8, vcc, s46, v4
	global_load_dwordx2 v[56:57], v[0:1], off
	global_load_dwordx2 v[58:59], v[2:3], off
	global_load_dwordx2 v[60:61], v[6:7], off
	v_addc_co_u32_e32 v9, vcc, 0, v5, vcc
	global_load_dwordx2 v[62:63], v[8:9], off
	s_nop 0
	global_load_dwordx2 v[0:1], v[0:1], off offset:2048
	s_nop 0
	global_load_dwordx2 v[4:5], v[2:3], off offset:2048
	s_nop 0
	global_load_dwordx2 v[6:7], v[6:7], off offset:2048
	s_nop 0
	global_load_dwordx2 v[8:9], v[8:9], off offset:2048
	v_or_b32_e32 v2, 1, v46
	v_mad_i64_i32 v[2:3], s[6:7], v2, s33, v[44:45]
	v_lshl_add_u64 v[2:3], v[2:3], 0, s[4:5]
	v_or_b32_e32 v10, 1, v47
	v_lshl_add_u64 v[2:3], v[2:3], 0, v[154:155]
	v_mad_i64_i32 v[10:11], s[6:7], v10, s33, v[44:45]
	v_add_co_u32_e32 v12, vcc, s46, v2
	v_lshl_add_u64 v[10:11], v[10:11], 0, s[4:5]
	v_or_b32_e32 v14, 1, v50
	v_addc_co_u32_e32 v13, vcc, 0, v3, vcc
	v_lshl_add_u64 v[10:11], v[10:11], 0, v[154:155]
	v_mad_i64_i32 v[14:15], s[6:7], v14, s33, v[44:45]
	v_add_co_u32_e32 v16, vcc, s46, v10
	v_lshl_add_u64 v[14:15], v[14:15], 0, s[4:5]
	v_or_b32_e32 v20, 1, v51
	v_addc_co_u32_e32 v17, vcc, 0, v11, vcc
	v_lshl_add_u64 v[14:15], v[14:15], 0, v[154:155]
	v_mad_i64_i32 v[20:21], s[6:7], v20, s33, v[44:45]
	v_add_co_u32_e32 v18, vcc, s46, v14
	v_lshl_add_u64 v[20:21], v[20:21], 0, s[4:5]
	s_nop 0
	v_addc_co_u32_e32 v19, vcc, 0, v15, vcc
	v_lshl_add_u64 v[20:21], v[20:21], 0, v[154:155]
	v_add_co_u32_e32 v26, vcc, s46, v20
	global_load_dwordx2 v[2:3], v[12:13], off
	global_load_dwordx2 v[10:11], v[16:17], off
	global_load_dwordx2 v[14:15], v[18:19], off
	v_addc_co_u32_e32 v27, vcc, 0, v21, vcc
	global_load_dwordx2 v[24:25], v[26:27], off
	global_load_dwordx2 v[20:21], v[12:13], off offset:2048
	global_load_dwordx2 v[22:23], v[16:17], off offset:2048
	s_nop 0
	global_load_dwordx2 v[12:13], v[18:19], off offset:2048
	global_load_dwordx2 v[16:17], v[26:27], off offset:2048
	v_or_b32_e32 v18, 2, v46
	v_mad_i64_i32 v[18:19], s[6:7], v18, s33, v[44:45]
	v_lshl_add_u64 v[18:19], v[18:19], 0, s[4:5]
	v_or_b32_e32 v26, 2, v47
	v_lshl_add_u64 v[18:19], v[18:19], 0, v[154:155]
	v_mad_i64_i32 v[26:27], s[6:7], v26, s33, v[44:45]
	v_add_co_u32_e32 v30, vcc, s46, v18
	v_lshl_add_u64 v[26:27], v[26:27], 0, s[4:5]
	v_or_b32_e32 v28, 2, v50
	v_addc_co_u32_e32 v31, vcc, 0, v19, vcc
	v_lshl_add_u64 v[26:27], v[26:27], 0, v[154:155]
	v_mad_i64_i32 v[28:29], s[6:7], v28, s33, v[44:45]
	v_add_co_u32_e32 v32, vcc, s46, v26
	v_lshl_add_u64 v[28:29], v[28:29], 0, s[4:5]
	v_or_b32_e32 v36, 2, v51
	v_addc_co_u32_e32 v33, vcc, 0, v27, vcc
	v_lshl_add_u64 v[28:29], v[28:29], 0, v[154:155]
	v_mad_i64_i32 v[36:37], s[6:7], v36, s33, v[44:45]
	v_add_co_u32_e32 v34, vcc, s46, v28
	v_lshl_add_u64 v[36:37], v[36:37], 0, s[4:5]
	s_nop 0
	v_addc_co_u32_e32 v35, vcc, 0, v29, vcc
	v_lshl_add_u64 v[36:37], v[36:37], 0, v[154:155]
	v_add_co_u32_e32 v42, vcc, s46, v36
	global_load_dwordx2 v[18:19], v[30:31], off
	global_load_dwordx2 v[26:27], v[32:33], off
	global_load_dwordx2 v[28:29], v[34:35], off
	v_addc_co_u32_e32 v43, vcc, 0, v37, vcc
	global_load_dwordx2 v[36:37], v[42:43], off
	global_load_dwordx2 v[38:39], v[30:31], off offset:2048
	global_load_dwordx2 v[40:41], v[32:33], off offset:2048
	s_nop 0
	global_load_dwordx2 v[30:31], v[34:35], off offset:2048
	global_load_dwordx2 v[32:33], v[42:43], off offset:2048
	v_or_b32_e32 v34, 3, v46
	v_mad_i64_i32 v[34:35], s[6:7], v34, s33, v[44:45]
	v_lshl_add_u64 v[34:35], v[34:35], 0, s[4:5]
	v_or_b32_e32 v42, 3, v47
	v_lshl_add_u64 v[34:35], v[34:35], 0, v[154:155]
	v_mad_i64_i32 v[42:43], s[6:7], v42, s33, v[44:45]
	v_add_co_u32_e32 v48, vcc, s46, v34
	v_lshl_add_u64 v[42:43], v[42:43], 0, s[4:5]
	v_or_b32_e32 v46, 3, v50
	v_addc_co_u32_e32 v49, vcc, 0, v35, vcc
	v_lshl_add_u64 v[42:43], v[42:43], 0, v[154:155]
	v_mad_i64_i32 v[46:47], s[6:7], v46, s33, v[44:45]
	v_add_co_u32_e32 v52, vcc, s46, v42
	v_lshl_add_u64 v[46:47], v[46:47], 0, s[4:5]
	v_or_b32_e32 v50, 3, v51
	v_addc_co_u32_e32 v53, vcc, 0, v43, vcc
	v_lshl_add_u64 v[46:47], v[46:47], 0, v[154:155]
	v_mad_i64_i32 v[44:45], s[6:7], v50, s33, v[44:45]
	v_add_co_u32_e32 v64, vcc, s46, v46
	v_lshl_add_u64 v[44:45], v[44:45], 0, s[4:5]
	global_load_dwordx2 v[34:35], v[48:49], off
	global_load_dwordx2 v[42:43], v[52:53], off
	v_addc_co_u32_e32 v65, vcc, 0, v47, vcc
	v_lshl_add_u64 v[44:45], v[44:45], 0, v[154:155]
	global_load_dwordx2 v[46:47], v[64:65], off
	v_add_co_u32_e32 v66, vcc, s46, v44
	s_lshl_b32 s6, s10, 13
	s_nop 0
	v_addc_co_u32_e32 v67, vcc, 0, v45, vcc
	global_load_dwordx2 v[54:55], v[66:67], off
	global_load_dwordx2 v[50:51], v[48:49], off offset:2048
	s_nop 0
	global_load_dwordx2 v[52:53], v[52:53], off offset:2048
	s_nop 0
	global_load_dwordx2 v[44:45], v[64:65], off offset:2048
	global_load_dwordx2 v[48:49], v[66:67], off offset:2048
	s_waitcnt vmcnt(30)
	ds_write2_b64 v102, v[56:57], v[58:59] offset1:72
	s_waitcnt vmcnt(28)
	ds_write2_b64 v102, v[60:61], v[62:63] offset0:144 offset1:216
	v_add_u32_e32 v56, 0x800, v102
	s_waitcnt vmcnt(26)
	ds_write2_b64 v56, v[0:1], v[4:5] offset0:32 offset1:104
	s_waitcnt vmcnt(24)
	ds_write2_b64 v56, v[6:7], v[8:9] offset0:176 offset1:248
	v_add_u32_e32 v0, 0x1000, v102
	s_waitcnt vmcnt(22)
	ds_write2_b64 v0, v[2:3], v[10:11] offset0:64 offset1:136
	v_add_u32_e32 v0, 0x1400, v102
	s_waitcnt vmcnt(20)
	ds_write2_b64 v0, v[14:15], v[24:25] offset0:80 offset1:152
	v_add_u32_e32 v0, 0x1800, v102
	s_waitcnt vmcnt(18)
	ds_write2_b64 v0, v[20:21], v[22:23] offset0:96 offset1:168
	v_add_u32_e32 v0, 0x1c00, v102
	s_waitcnt vmcnt(16)
	ds_write2_b64 v0, v[12:13], v[16:17] offset0:112 offset1:184
	v_add_u32_e32 v0, 0x2000, v102
	s_add_u32 s6, s3, s6
	s_addc_u32 s7, s8, 0
	v_mov_b32_e32 v87, v155
	v_mov_b32_e32 v89, v155
	v_mov_b32_e32 v91, v155
	s_add_u32 s22, s6, 0x1000
	s_addc_u32 s23, s7, 0
	v_lshl_add_u64 v[92:93], v[84:85], 0, s[4:5]
	s_waitcnt vmcnt(14)
	ds_write2_b64 v0, v[18:19], v[26:27] offset0:128 offset1:200
	v_add_u32_e32 v0, 0x2800, v102
	s_waitcnt vmcnt(12)
	ds_write2_b64 v0, v[28:29], v[36:37] offset0:16 offset1:88
	s_waitcnt vmcnt(10)
	ds_write2_b64 v0, v[38:39], v[40:41] offset0:160 offset1:232
	v_add_u32_e32 v0, 0x3000, v102
	s_waitcnt vmcnt(8)
	ds_write2_b64 v0, v[30:31], v[32:33] offset0:48 offset1:120
	v_add_u32_e32 v0, 0x3400, v102
	v_lshl_add_u64 v[32:33], s[6:7], 0, v[86:87]
	v_lshl_add_u64 v[32:33], v[32:33], 0, v[88:89]
	s_waitcnt vmcnt(6)
	ds_write2_b64 v0, v[34:35], v[42:43] offset0:64 offset1:136
	v_add_u32_e32 v0, 0x3800, v102
	v_lshl_add_u64 v[34:35], s[6:7], 0, v[90:91]
	v_lshl_add_u64 v[34:35], v[34:35], 0, v[88:89]
	s_add_u32 s6, s6, 0x1800
	s_addc_u32 s7, s7, 0
	s_waitcnt vmcnt(4)
	ds_write2_b64 v0, v[46:47], v[54:55] offset0:80 offset1:152
	v_add_u32_e32 v0, 0x3c00, v102
	s_waitcnt vmcnt(2)
	ds_write2_b64 v0, v[50:51], v[52:53] offset0:96 offset1:168
	v_add_u32_e32 v0, 0x4000, v102
	s_waitcnt vmcnt(0)
	ds_write2_b64 v0, v[44:45], v[48:49] offset0:112 offset1:184
	ds_read_b64_tr_b16 v[62:63], v94 offset:2304
	ds_read_b64_tr_b16 v[60:61], v94
	ds_read_b64_tr_b16 v[64:65], v94 offset:32
	ds_read_b64_tr_b16 v[66:67], v94 offset:2336
	ds_read_b64_tr_b16 v[68:69], v94 offset:64
	ds_read_b64_tr_b16 v[70:71], v94 offset:2368
	ds_read_b64_tr_b16 v[72:73], v94 offset:96
	ds_read_b64_tr_b16 v[74:75], v94 offset:2400
	ds_read_b64_tr_b16 v[36:37], v94 offset:4608
	ds_read_b64_tr_b16 v[38:39], v94 offset:6912
	ds_read_b64_tr_b16 v[40:41], v94 offset:4640
	ds_read_b64_tr_b16 v[42:43], v94 offset:6944
	ds_read_b64_tr_b16 v[44:45], v94 offset:4672
	ds_read_b64_tr_b16 v[46:47], v94 offset:6976
	ds_read_b64_tr_b16 v[48:49], v94 offset:4704
	ds_read_b64_tr_b16 v[50:51], v94 offset:7008
	ds_read_b64_tr_b16 v[16:17], v94 offset:9216
	ds_read_b64_tr_b16 v[18:19], v94 offset:11520
	ds_read_b64_tr_b16 v[20:21], v94 offset:9248
	ds_read_b64_tr_b16 v[22:23], v94 offset:11552
	ds_read_b64_tr_b16 v[24:25], v94 offset:9280
	ds_read_b64_tr_b16 v[26:27], v94 offset:11584
	ds_read_b64_tr_b16 v[28:29], v94 offset:9312
	ds_read_b64_tr_b16 v[30:31], v94 offset:11616
	ds_read_b64_tr_b16 v[0:1], v94 offset:13824
	ds_read_b64_tr_b16 v[2:3], v94 offset:16128
	ds_read_b64_tr_b16 v[4:5], v94 offset:13856
	ds_read_b64_tr_b16 v[6:7], v94 offset:16160
	ds_read_b64_tr_b16 v[8:9], v94 offset:13888
	ds_read_b64_tr_b16 v[10:11], v94 offset:16192
	ds_read_b64_tr_b16 v[12:13], v94 offset:13920
	ds_read_b64_tr_b16 v[14:15], v94 offset:16224
	global_load_dwordx2 v[104:105], v[32:33], off
	global_load_dwordx2 v[106:107], v[32:33], off offset:32
	global_load_dwordx2 v[108:109], v[34:35], off
	global_load_dwordx2 v[110:111], v[34:35], off offset:32
	global_load_dwordx2 v[112:113], v[32:33], off offset:2048
	global_load_dwordx2 v[114:115], v[32:33], off offset:2080
	global_load_dwordx2 v[80:81], v[34:35], off offset:2048
	global_load_dwordx2 v[82:83], v[34:35], off offset:2080
	v_lshl_add_u64 v[32:33], s[22:23], 0, v[86:87]
	v_lshl_add_u64 v[32:33], v[32:33], 0, v[88:89]
	global_load_dwordx2 v[76:77], v[32:33], off
	global_load_dwordx2 v[78:79], v[32:33], off offset:32
	v_lshl_add_u64 v[32:33], s[22:23], 0, v[90:91]
	v_lshl_add_u64 v[32:33], v[32:33], 0, v[88:89]
	global_load_dwordx2 v[56:57], v[32:33], off
	global_load_dwordx2 v[58:59], v[32:33], off offset:32
	v_lshl_add_u64 v[32:33], s[6:7], 0, v[86:87]
	v_lshl_add_u64 v[32:33], v[32:33], 0, v[88:89]
	global_load_dwordx2 v[52:53], v[32:33], off
	global_load_dwordx2 v[54:55], v[32:33], off offset:32
	v_lshl_add_u64 v[32:33], s[6:7], 0, v[90:91]
	v_lshl_add_u64 v[34:35], v[32:33], 0, v[88:89]
	global_load_dwordx2 v[32:33], v[34:35], off
	s_nop 0
	global_load_dwordx2 v[34:35], v[34:35], off offset:32
	s_lshl_b32 s6, s11, 4
	v_or_b32_e32 v89, s6, v100
	v_lshl_or_b32 v87, s10, 3, v95
	s_waitcnt vmcnt(14) lgkmcnt(14)
	v_mfma_f32_16x16x32_bf16 v[116:119], v[60:63], v[104:107], 0
	v_lshl_add_u32 v89, v89, 8, v89
	v_add_u32_e32 v128, v87, v89
	v_ashrrev_i32_e32 v129, 31, v128
	v_mfma_f32_16x16x32_bf16 v[120:123], v[64:67], v[104:107], 0
	v_lshlrev_b64 v[128:129], 11, v[128:129]
	v_lshl_add_u64 v[128:129], v[92:93], 0, v[128:129]
	s_nop 1
	v_cvt_pk_bf16_f32 v116, v116, v117
	v_mfma_f32_16x16x32_bf16 v[124:127], v[68:71], v[104:107], 0
	v_cvt_pk_bf16_f32 v117, v118, v119
	ds_write_b64 v216, v[116:117]
	v_cvt_pk_bf16_f32 v116, v120, v121
	v_mfma_f32_16x16x32_bf16 v[104:107], v[72:75], v[104:107], 0
	v_cvt_pk_bf16_f32 v117, v122, v123
	ds_write_b64 v216, v[116:117] offset:32
	s_nop 1
	v_cvt_pk_bf16_f32 v116, v124, v125
	v_cvt_pk_bf16_f32 v117, v126, v127
	ds_write_b64 v216, v[116:117] offset:64
	s_nop 0
	v_cvt_pk_bf16_f32 v104, v104, v105
	v_cvt_pk_bf16_f32 v105, v106, v107
	ds_write_b64 v216, v[104:105] offset:96
	v_readfirstlane_b32 s98, v128
	v_readfirstlane_b32 s99, v129
	s_waitcnt lgkmcnt(0)
	ds_read_b64 v[220:221], v217
	ds_read_b64 v[222:223], v217 offset:576
	ds_read_b64 v[224:225], v217 offset:1152
	ds_read_b64 v[226:227], v217 offset:1728
	s_waitcnt lgkmcnt(3)
	global_store_dwordx2 v218, v[220:221], s[98:99]
	s_waitcnt lgkmcnt(2)
	global_store_dwordx2 v219, v[222:223], s[98:99]
	s_waitcnt lgkmcnt(1)
	global_store_dwordx2 v228, v[224:225], s[98:99]
	s_waitcnt lgkmcnt(0)
	global_store_dwordx2 v229, v[226:227], s[98:99]
	s_waitcnt vmcnt(16)
	v_mfma_f32_16x16x32_bf16 v[104:107], v[60:63], v[108:111], 0
	v_or_b32_e32 v60, s6, v101
	v_lshl_add_u32 v60, v60, 8, v60
	v_or_b32_e32 v61, 2, v87
	v_mfma_f32_16x16x32_bf16 v[62:65], v[64:67], v[108:111], 0
	s_add_i32 s9, s9, s28
	s_nop 2
	v_cvt_pk_bf16_f32 v104, v104, v105
	v_cvt_pk_bf16_f32 v105, v106, v107
	v_mfma_f32_16x16x32_bf16 v[66:69], v[68:71], v[108:111], 0
	s_add_i32 s2, s2, s12
	v_cvt_pk_bf16_f32 v62, v62, v63
	v_cvt_pk_bf16_f32 v63, v64, v65
	v_mfma_f32_16x16x32_bf16 v[70:73], v[72:75], v[108:111], 0
	v_add_u32_e32 v74, v87, v60
	v_ashrrev_i32_e32 v75, 31, v74
	v_lshlrev_b64 v[74:75], 11, v[74:75]
	v_lshl_add_u64 v[74:75], v[92:93], 0, v[74:75]
	ds_write_b64 v216, v[62:63] offset:32
	v_cvt_pk_bf16_f32 v62, v66, v67
	v_cvt_pk_bf16_f32 v63, v68, v69
	ds_write_b64 v216, v[62:63] offset:64
	v_cvt_pk_bf16_f32 v62, v70, v71
	v_cvt_pk_bf16_f32 v63, v72, v73
	ds_write_b64 v216, v[62:63] offset:96
	s_waitcnt vmcnt(14)
	v_mfma_f32_16x16x32_bf16 v[62:65], v[36:39], v[112:115], 0
	ds_write_b64 v216, v[104:105]
	v_readfirstlane_b32 s98, v74
	v_readfirstlane_b32 s99, v75
	s_waitcnt lgkmcnt(0)
	ds_read_b64 v[220:221], v217
	ds_read_b64 v[222:223], v217 offset:576
	ds_read_b64 v[224:225], v217 offset:1152
	ds_read_b64 v[226:227], v217 offset:1728
	s_waitcnt lgkmcnt(3)
	global_store_dwordx2 v218, v[220:221], s[98:99]
	s_waitcnt lgkmcnt(2)
	global_store_dwordx2 v219, v[222:223], s[98:99]
	s_waitcnt lgkmcnt(1)
	global_store_dwordx2 v228, v[224:225], s[98:99]
	s_waitcnt lgkmcnt(0)
	global_store_dwordx2 v229, v[226:227], s[98:99]
	v_add_u32_e32 v74, v61, v89
	v_ashrrev_i32_e32 v75, 31, v74
	v_mfma_f32_16x16x32_bf16 v[66:69], v[40:43], v[112:115], 0
	v_lshlrev_b64 v[74:75], 11, v[74:75]
	v_lshl_add_u64 v[74:75], v[92:93], 0, v[74:75]
	s_nop 1
	v_cvt_pk_bf16_f32 v62, v62, v63
	v_mfma_f32_16x16x32_bf16 v[70:73], v[44:47], v[112:115], 0
	v_cvt_pk_bf16_f32 v63, v64, v65
	ds_write_b64 v216, v[62:63]
	v_cvt_pk_bf16_f32 v62, v66, v67
	v_mfma_f32_16x16x32_bf16 v[104:107], v[48:51], v[112:115], 0
	v_cvt_pk_bf16_f32 v63, v68, v69
	ds_write_b64 v216, v[62:63] offset:32
	s_nop 1
	v_cvt_pk_bf16_f32 v62, v70, v71
	v_cvt_pk_bf16_f32 v63, v72, v73
	ds_write_b64 v216, v[62:63] offset:64
	s_nop 0
	v_cvt_pk_bf16_f32 v62, v104, v105
	v_cvt_pk_bf16_f32 v63, v106, v107
	s_waitcnt vmcnt(16)
	v_mfma_f32_16x16x32_bf16 v[36:39], v[36:39], v[80:83], 0
	ds_write_b64 v216, v[62:63] offset:96
	v_readfirstlane_b32 s98, v74
	v_readfirstlane_b32 s99, v75
	s_waitcnt lgkmcnt(0)
	ds_read_b64 v[220:221], v217
	ds_read_b64 v[222:223], v217 offset:576
	ds_read_b64 v[224:225], v217 offset:1152
	ds_read_b64 v[226:227], v217 offset:1728
	s_waitcnt lgkmcnt(3)
	global_store_dwordx2 v218, v[220:221], s[98:99]
	s_waitcnt lgkmcnt(2)
	global_store_dwordx2 v219, v[222:223], s[98:99]
	s_waitcnt lgkmcnt(1)
	global_store_dwordx2 v228, v[224:225], s[98:99]
	s_waitcnt lgkmcnt(0)
	global_store_dwordx2 v229, v[226:227], s[98:99]
	v_add_u32_e32 v62, v61, v60
	v_ashrrev_i32_e32 v63, 31, v62
	v_mfma_f32_16x16x32_bf16 v[40:43], v[40:43], v[80:83], 0
	v_lshlrev_b64 v[62:63], 11, v[62:63]
	v_lshl_add_u64 v[62:63], v[92:93], 0, v[62:63]
	s_nop 1
	v_cvt_pk_bf16_f32 v36, v36, v37
	v_mfma_f32_16x16x32_bf16 v[44:47], v[44:47], v[80:83], 0
	v_cvt_pk_bf16_f32 v37, v38, v39
	ds_write_b64 v216, v[36:37]
	v_cvt_pk_bf16_f32 v36, v40, v41
	v_mfma_f32_16x16x32_bf16 v[48:51], v[48:51], v[80:83], 0
	v_cvt_pk_bf16_f32 v37, v42, v43
	ds_write_b64 v216, v[36:37] offset:32
	s_nop 1
	v_cvt_pk_bf16_f32 v36, v44, v45
	v_cvt_pk_bf16_f32 v37, v46, v47
	ds_write_b64 v216, v[36:37] offset:64
	s_nop 0
	v_cvt_pk_bf16_f32 v36, v48, v49
	v_cvt_pk_bf16_f32 v37, v50, v51
	ds_write_b64 v216, v[36:37] offset:96
	v_readfirstlane_b32 s98, v62
	v_readfirstlane_b32 s99, v63
	s_waitcnt lgkmcnt(0)
	ds_read_b64 v[220:221], v217
	ds_read_b64 v[222:223], v217 offset:576
	ds_read_b64 v[224:225], v217 offset:1152
	ds_read_b64 v[226:227], v217 offset:1728
	s_waitcnt lgkmcnt(3)
	global_store_dwordx2 v218, v[220:221], s[98:99]
	s_waitcnt lgkmcnt(2)
	global_store_dwordx2 v219, v[222:223], s[98:99]
	s_waitcnt lgkmcnt(1)
	global_store_dwordx2 v228, v[224:225], s[98:99]
	s_waitcnt lgkmcnt(0)
	global_store_dwordx2 v229, v[226:227], s[98:99]
	s_waitcnt vmcnt(22)
	v_mfma_f32_16x16x32_bf16 v[36:39], v[16:19], v[76:79], 0
	v_or_b32_e32 v61, 4, v87
	v_add_u32_e32 v62, v61, v89
	v_ashrrev_i32_e32 v63, 31, v62
	s_waitcnt lgkmcnt(12)
	v_mfma_f32_16x16x32_bf16 v[40:43], v[20:23], v[76:79], 0
	v_lshlrev_b64 v[62:63], 11, v[62:63]
	v_lshl_add_u64 v[62:63], v[92:93], 0, v[62:63]
	s_nop 0
	v_cvt_pk_bf16_f32 v36, v36, v37
	s_waitcnt lgkmcnt(10)
	v_mfma_f32_16x16x32_bf16 v[44:47], v[24:27], v[76:79], 0
	v_cvt_pk_bf16_f32 v37, v38, v39
	ds_write_b64 v216, v[36:37]
	v_cvt_pk_bf16_f32 v36, v40, v41
	s_waitcnt lgkmcnt(8)
	v_mfma_f32_16x16x32_bf16 v[48:51], v[28:31], v[76:79], 0
	v_cvt_pk_bf16_f32 v37, v42, v43
	ds_write_b64 v216, v[36:37] offset:32
	s_nop 0
	v_cvt_pk_bf16_f32 v36, v44, v45
	v_cvt_pk_bf16_f32 v37, v46, v47
	ds_write_b64 v216, v[36:37] offset:64
	s_nop 1
	v_cvt_pk_bf16_f32 v36, v48, v49
	v_cvt_pk_bf16_f32 v37, v50, v51
	s_waitcnt vmcnt(20)
	v_mfma_f32_16x16x32_bf16 v[16:19], v[16:19], v[56:59], 0
	ds_write_b64 v216, v[36:37] offset:96
	v_readfirstlane_b32 s98, v62
	v_readfirstlane_b32 s99, v63
	s_waitcnt lgkmcnt(0)
	ds_read_b64 v[220:221], v217
	ds_read_b64 v[222:223], v217 offset:576
	ds_read_b64 v[224:225], v217 offset:1152
	ds_read_b64 v[226:227], v217 offset:1728
	s_waitcnt lgkmcnt(3)
	global_store_dwordx2 v218, v[220:221], s[98:99]
	s_waitcnt lgkmcnt(2)
	global_store_dwordx2 v219, v[222:223], s[98:99]
	s_waitcnt lgkmcnt(1)
	global_store_dwordx2 v228, v[224:225], s[98:99]
	s_waitcnt lgkmcnt(0)
	global_store_dwordx2 v229, v[226:227], s[98:99]
	v_add_u32_e32 v36, v61, v60
	v_ashrrev_i32_e32 v37, 31, v36
	v_mfma_f32_16x16x32_bf16 v[20:23], v[20:23], v[56:59], 0
	v_lshlrev_b64 v[36:37], 11, v[36:37]
	v_lshl_add_u64 v[36:37], v[92:93], 0, v[36:37]
	s_nop 1
	v_cvt_pk_bf16_f32 v16, v16, v17
	v_mfma_f32_16x16x32_bf16 v[24:27], v[24:27], v[56:59], 0
	v_cvt_pk_bf16_f32 v17, v18, v19
	ds_write_b64 v216, v[16:17]
	v_cvt_pk_bf16_f32 v16, v20, v21
	v_mfma_f32_16x16x32_bf16 v[28:31], v[28:31], v[56:59], 0
	v_cvt_pk_bf16_f32 v17, v22, v23
	ds_write_b64 v216, v[16:17] offset:32
	s_nop 1
	v_cvt_pk_bf16_f32 v16, v24, v25
	v_cvt_pk_bf16_f32 v17, v26, v27
	ds_write_b64 v216, v[16:17] offset:64
	s_nop 0
	v_cvt_pk_bf16_f32 v16, v28, v29
	v_cvt_pk_bf16_f32 v17, v30, v31
	ds_write_b64 v216, v[16:17] offset:96
	v_readfirstlane_b32 s98, v36
	v_readfirstlane_b32 s99, v37
	s_waitcnt lgkmcnt(0)
	ds_read_b64 v[220:221], v217
	ds_read_b64 v[222:223], v217 offset:576
	ds_read_b64 v[224:225], v217 offset:1152
	ds_read_b64 v[226:227], v217 offset:1728
	s_waitcnt lgkmcnt(3)
	global_store_dwordx2 v218, v[220:221], s[98:99]
	s_waitcnt lgkmcnt(2)
	global_store_dwordx2 v219, v[222:223], s[98:99]
	s_waitcnt lgkmcnt(1)
	global_store_dwordx2 v228, v[224:225], s[98:99]
	s_waitcnt lgkmcnt(0)
	global_store_dwordx2 v229, v[226:227], s[98:99]
	s_waitcnt vmcnt(26) lgkmcnt(6)
	v_mfma_f32_16x16x32_bf16 v[16:19], v[0:3], v[52:55], 0
	v_or_b32_e32 v38, 6, v87
	v_add_u32_e32 v36, v38, v89
	v_ashrrev_i32_e32 v37, 31, v36
	s_waitcnt lgkmcnt(4)
	v_mfma_f32_16x16x32_bf16 v[20:23], v[4:7], v[52:55], 0
	v_lshlrev_b64 v[36:37], 11, v[36:37]
	v_lshl_add_u64 v[36:37], v[92:93], 0, v[36:37]
	s_nop 0
	v_cvt_pk_bf16_f32 v16, v16, v17
	s_waitcnt lgkmcnt(2)
	v_mfma_f32_16x16x32_bf16 v[24:27], v[8:11], v[52:55], 0
	v_cvt_pk_bf16_f32 v17, v18, v19
	ds_write_b64 v216, v[16:17]
	v_cvt_pk_bf16_f32 v16, v20, v21
	s_waitcnt lgkmcnt(0)
	v_mfma_f32_16x16x32_bf16 v[28:31], v[12:15], v[52:55], 0
	v_cvt_pk_bf16_f32 v17, v22, v23
	ds_write_b64 v216, v[16:17] offset:32
	s_nop 0
	v_cvt_pk_bf16_f32 v16, v24, v25
	v_cvt_pk_bf16_f32 v17, v26, v27
	ds_write_b64 v216, v[16:17] offset:64
	s_nop 1
	v_cvt_pk_bf16_f32 v16, v28, v29
	v_cvt_pk_bf16_f32 v17, v30, v31
	s_waitcnt vmcnt(24)
	v_mfma_f32_16x16x32_bf16 v[0:3], v[0:3], v[32:35], 0
	ds_write_b64 v216, v[16:17] offset:96
	v_readfirstlane_b32 s98, v36
	v_readfirstlane_b32 s99, v37
	s_waitcnt lgkmcnt(0)
	ds_read_b64 v[220:221], v217
	ds_read_b64 v[222:223], v217 offset:576
	ds_read_b64 v[224:225], v217 offset:1152
	ds_read_b64 v[226:227], v217 offset:1728
	s_waitcnt lgkmcnt(3)
	global_store_dwordx2 v218, v[220:221], s[98:99]
	s_waitcnt lgkmcnt(2)
	global_store_dwordx2 v219, v[222:223], s[98:99]
	s_waitcnt lgkmcnt(1)
	global_store_dwordx2 v228, v[224:225], s[98:99]
	s_waitcnt lgkmcnt(0)
	global_store_dwordx2 v229, v[226:227], s[98:99]
	v_add_u32_e32 v16, v38, v60
	v_ashrrev_i32_e32 v17, 31, v16
	v_mfma_f32_16x16x32_bf16 v[4:7], v[4:7], v[32:35], 0
	v_lshlrev_b64 v[16:17], 11, v[16:17]
	v_lshl_add_u64 v[16:17], v[92:93], 0, v[16:17]
	s_nop 1
	v_cvt_pk_bf16_f32 v0, v0, v1
	v_mfma_f32_16x16x32_bf16 v[8:11], v[8:11], v[32:35], 0
	v_cvt_pk_bf16_f32 v1, v2, v3
	ds_write_b64 v216, v[0:1]
	v_cvt_pk_bf16_f32 v0, v4, v5
	v_mfma_f32_16x16x32_bf16 v[12:15], v[12:15], v[32:35], 0
	v_cvt_pk_bf16_f32 v1, v6, v7
	ds_write_b64 v216, v[0:1] offset:32
	s_nop 1
	v_cvt_pk_bf16_f32 v0, v8, v9
	v_cvt_pk_bf16_f32 v1, v10, v11
	ds_write_b64 v216, v[0:1] offset:64
	s_nop 0
	v_cvt_pk_bf16_f32 v0, v12, v13
	v_cvt_pk_bf16_f32 v1, v14, v15
	ds_write_b64 v216, v[0:1] offset:96
	v_readfirstlane_b32 s98, v16
	v_readfirstlane_b32 s99, v17
	s_waitcnt lgkmcnt(0)
	ds_read_b64 v[220:221], v217
	ds_read_b64 v[222:223], v217 offset:576
	ds_read_b64 v[224:225], v217 offset:1152
	ds_read_b64 v[226:227], v217 offset:1728
	s_waitcnt lgkmcnt(3)
	global_store_dwordx2 v218, v[220:221], s[98:99]
	s_waitcnt lgkmcnt(2)
	global_store_dwordx2 v219, v[222:223], s[98:99]
	s_waitcnt lgkmcnt(1)
	global_store_dwordx2 v228, v[224:225], s[98:99]
	s_waitcnt lgkmcnt(0)
	global_store_dwordx2 v229, v[226:227], s[98:99]
	s_cmpk_gt_i32 s9, 0xfff
	s_cbranch_scc0 .LBB0_134
